# v53: v50 + grid barrier B3 (P2->P3) replaced by dependency counters: FoX cumsum runs first in P2 and FoX items wait only for it; GDN scan items wait for all prep (one L2 writeback per XCD)
# speedup vs baseline: 1.0243x; 1.0127x over previous
; DI void fox_cumsum(const Params& P, int bh, unsigned char* smem, int tt) {
;     const int tid = tt, lane = tid & 63, wave = tid >> 6;
;     const int b = bh >> 3, hh = bh & 7;
;     float* wsum = (float*)smem;
;     const float* gates = (const float*)(P.ws + OFF_GATES);
;     const float bf = P.in[9][hh];
;     float v[8]; float run = 0.f;
; #pragma unroll
;     for (int e = 0; e < 8; ++e) {
;         const float xx = gates[((size_t)b * TSEQ + tid * 8 + e) * 16 + 8 + hh] + bf;
;         const float ls = fminf(xx, 0.f) - log1pf(__expf(-fabsf(xx)));
;         run += ls; v[e] = run;
;     }
; __global__ void __launch_bounds__(512, 2) fwd_mega(Params P) {
;     ...
;     for (int rep = 0; rep < NREP(2); ++rep)
;     {
;     for (int base = bid * 2; base < 1024 + 64; base += nblk * 2) {
;         PHASE_IDS
;         const int it = base + team;
;         if (it < 1024) prep_chunk(P, it, smem, tt); else fox_cumsum(P, it - 1024, smem, tt);
;     }
.LBB0_219:
	s_or_b64 exec, exec, s[88:89]
	s_cmp_lt_u32 s33, 32
	s_cbranch_scc0 .Lcs_skip
	s_cmp_lt_u32 s86, 64
	s_cbranch_scc0 .Lcs_skip
	s_waitcnt vmcnt(0)
	s_barrier
	v_readlane_b32 s99, v255, 39
	s_nop 3
	s_cmp_lg_u32 s99, 0
	s_cbranch_scc1 .Lcs_skip
	buffer_wbl2 sc1
	s_waitcnt vmcnt(0)
	s_add_u32 s100, s80, 0x1d83c40
	s_addc_u32 s101, s81, 0
	s_mov_b64 s[0:1], exec
	s_mov_b64 exec, 1
	v_mov_b32_e32 v198, 0
	v_mov_b32_e32 v199, 1
	global_atomic_add v198, v199, s[100:101]
	s_mov_b64 exec, s[0:1]
.Lcs_skip:
	s_add_i32 s86, s86, s85
	s_cmpk_gt_i32 s86, 0x43f
	s_cbranch_scc1 .LBB0_477
.LBB0_220:
	v_readlane_b32 s0, v255, 39
	v_mbcnt_lo_u32_b32 v126, -1, 0
	v_mbcnt_hi_u32_b32 v126, -1, v126
	s_nop 0
	v_and_b32_e32 v123, 63, v126
	v_add_u32_e32 v132, s0, v126
	v_ashrrev_i32_e32 v2, 8, v132
	s_mov_b32 s0, 0x12c00
	v_mad_i32_i24 v125, v2, s0, 0
	v_add_u32_e32 v84, s86, v2
	v_subrev_u32_e32 v84, 64, v84
	v_add_u32_e32 v0, 0x440, v84
	v_cmp_gt_i32_e32 vcc, 0, v84
	s_nop 1
	v_cndmask_b32_e32 v84, v84, v0, vcc
	s_movk_i32 s0, 0x3ff
	v_and_b32_e32 v124, 0xff, v132
	v_cmp_lt_i32_e32 vcc, s0, v84
	s_and_saveexec_b64 s[0:1], vcc
	s_xor_b64 s[0:1], exec, s[0:1]
	s_cbranch_execz .LBB0_228
	v_and_b32_e32 v1, 7, v84
	v_lshlrev_b32_e32 v80, 2, v1
	global_load_dword v1, v80, s[46:47]
	v_add_u32_e32 v0, 0xfffffc00, v84
	v_lshrrev_b32_e32 v2, 3, v0
	v_mov_b32_e32 v3, v81
	v_lshl_add_u64 v[4:5], s[12:13], 0, v[80:81]
	v_lshlrev_b64 v[2:3], 17, v[2:3]
	v_lshlrev_b32_e32 v80, 9, v124
	v_lshl_add_u64 v[2:3], v[4:5], 0, v[2:3]
	v_lshl_add_u64 v[2:3], v[2:3], 0, v[80:81]
	global_load_dword v4, v[2:3], off
	global_load_dword v11, v[2:3], off offset:64
	global_load_dword v5, v[2:3], off offset:128
	global_load_dword v6, v[2:3], off offset:192
	global_load_dword v7, v[2:3], off offset:256
	global_load_dword v8, v[2:3], off offset:320
	global_load_dword v9, v[2:3], off offset:384
	global_load_dword v10, v[2:3], off offset:448
	s_movk_i32 s2, 0x80
	s_waitcnt vmcnt(7)
	v_add_f32_e32 v2, v1, v4
	v_mul_f32_e64 v4, |v2|, s92
	s_waitcnt vmcnt(6)
	v_add_f32_e32 v3, v1, v11
	v_exp_f32_e32 v4, v4
	v_mul_f32_e64 v11, |v3|, s92
	v_exp_f32_e32 v11, v11
	v_min_f32_e32 v14, 0, v2
	v_add_f32_e32 v16, 1.0, v4
	v_min_f32_e32 v15, 0, v3
	v_frexp_mant_f32_e32 v19, v16
	v_cvt_f64_f32_e32 v[2:3], v16
	v_add_f32_e32 v17, 1.0, v11
	v_add_f32_e32 v18, -1.0, v16
	v_frexp_exp_i32_f64_e32 v2, v[2:3]
	v_cmp_gt_f32_e32 vcc, s93, v19
	v_add_f32_e32 v20, -1.0, v17
	v_frexp_mant_f32_e32 v21, v17
	v_cvt_f64_f32_e32 v[12:13], v17
	v_sub_f32_e32 v22, v18, v16
	v_subbrev_co_u32_e32 v2, vcc, 0, v2, vcc
	v_sub_f32_e32 v18, v4, v18
	v_sub_f32_e32 v3, v20, v17
	v_frexp_exp_i32_f64_e32 v12, v[12:13]
	v_add_f32_e32 v13, 1.0, v22
	v_cmp_gt_f32_e32 vcc, s93, v21
	v_sub_f32_e32 v20, v11, v20
	v_add_f32_e32 v3, 1.0, v3
	v_subbrev_co_u32_e32 v12, vcc, 0, v12, vcc
	v_add_f32_e32 v13, v18, v13
	v_sub_u32_e32 v18, 0, v2
	v_cvt_f32_i32_e32 v2, v2
	v_add_f32_e32 v3, v20, v3
	v_sub_u32_e32 v19, 0, v12
	v_ldexp_f32 v16, v16, v18
	v_ldexp_f32 v13, v13, v18
	v_ldexp_f32 v17, v17, v19
	v_ldexp_f32 v3, v3, v19
	v_add_f32_e32 v18, -1.0, v16
	v_add_f32_e32 v19, 1.0, v16
	v_add_f32_e32 v20, 1.0, v18
	v_add_f32_e32 v21, -1.0, v19
	v_sub_f32_e32 v20, v16, v20
	v_sub_f32_e32 v16, v16, v21
	v_mul_f32_e32 v21, 0x3f317218, v2
	v_add_f32_e32 v20, v13, v20
	v_add_f32_e32 v13, v13, v16
	v_fma_f32 v16, v2, s94, -v21
	v_add_f32_e32 v22, v18, v20
	v_add_f32_e32 v23, v19, v13
	v_fmac_f32_e32 v16, 0xb102e308, v2
	v_sub_f32_e32 v2, v22, v18
	v_sub_f32_e32 v18, v23, v19
	v_rcp_f32_e32 v19, v23
	v_add_f32_e32 v24, v21, v16
	v_sub_f32_e32 v13, v13, v18
	v_sub_f32_e32 v18, v24, v21
	v_sub_f32_e32 v16, v16, v18
	v_mul_f32_e32 v18, v22, v19
	v_sub_f32_e32 v2, v20, v2
	v_mul_f32_e32 v20, v23, v18
	v_fma_f32 v21, v18, v23, -v20
	v_fmac_f32_e32 v21, v18, v13
	v_add_f32_e32 v25, v20, v21
	v_sub_f32_e32 v26, v22, v25
	v_sub_f32_e32 v20, v25, v20
	v_sub_f32_e32 v22, v22, v26
	v_sub_f32_e32 v20, v20, v21
	v_sub_f32_e32 v21, v22, v25
	v_add_f32_e32 v2, v2, v21
	v_add_f32_e32 v2, v20, v2
	v_add_f32_e32 v20, v26, v2
	v_mul_f32_e32 v21, v19, v20
	v_sub_f32_e32 v22, v26, v20
	v_mul_f32_e32 v25, v23, v21
	v_add_f32_e32 v2, v2, v22
	v_add_f32_e32 v22, v18, v21
	v_fma_f32 v23, v21, v23, -v25
	v_sub_f32_e32 v18, v22, v18
	v_fmac_f32_e32 v23, v21, v13
	v_sub_f32_e32 v13, v21, v18
	v_add_f32_e32 v18, v25, v23
	v_sub_f32_e32 v21, v18, v25
	v_sub_f32_e32 v25, v20, v18
	v_sub_f32_e32 v20, v20, v25
	v_sub_f32_e32 v18, v20, v18
	v_sub_f32_e32 v21, v21, v23
	v_add_f32_e32 v2, v2, v18
	v_add_f32_e32 v2, v21, v2
	v_add_f32_e32 v2, v25, v2
	v_mul_f32_e32 v2, v19, v2
	v_add_f32_e32 v2, v13, v2
	v_add_f32_e32 v13, v22, v2
	v_mul_f32_e32 v18, v13, v13
	v_fmamk_f32 v21, v18, 0x3e9b6dac, v83
	v_sub_f32_e32 v19, v13, v22
	v_ldexp_f32 v20, v13, 1
	v_mul_f32_e32 v13, v13, v18
	v_fmaak_f32 v18, v18, v21, 0x3f2aaada
	v_mul_f32_e32 v13, v13, v18
	v_add_f32_e32 v18, v20, v13
	v_sub_f32_e32 v2, v2, v19
	v_sub_f32_e32 v19, v18, v20
	v_ldexp_f32 v2, v2, 1
	v_sub_f32_e32 v13, v13, v19
	v_add_f32_e32 v2, v2, v13
	v_add_f32_e32 v13, v18, v2
	v_sub_f32_e32 v18, v13, v18
	v_add_f32_e32 v19, v24, v13
	v_sub_f32_e32 v2, v2, v18
	v_sub_f32_e32 v18, v19, v24
	v_sub_f32_e32 v20, v19, v18
	v_sub_f32_e32 v13, v13, v18
	v_add_f32_e32 v18, v16, v2
	v_sub_f32_e32 v20, v24, v20
	v_sub_f32_e32 v21, v18, v16
	v_add_f32_e32 v13, v13, v20
	v_sub_f32_e32 v20, v18, v21
	v_sub_f32_e32 v2, v2, v21
	v_sub_f32_e32 v16, v16, v20
	v_add_f32_e32 v13, v18, v13
	v_add_f32_e32 v2, v2, v16
	v_add_f32_e32 v16, v19, v13
	v_sub_f32_e32 v18, v16, v19
	v_sub_f32_e32 v13, v13, v18
	v_add_f32_e32 v2, v2, v13
	v_add_f32_e32 v2, v16, v2
; DI void fox_cumsum(const Params& P, int bh, unsigned char* smem, int tt) {
;     ...
;     for (int e = 0; e < 8; ++e) {
;         const float xx = gates[((size_t)b * TSEQ + tid * 8 + e) * 16 + 8 + hh] + bf;
;         const float ls = fminf(xx, 0.f) - log1pf(__expf(-fabsf(xx)));
;         run += ls; v[e] = run;
;     }
	v_cmp_neq_f32_e32 vcc, s95, v4
	v_add_f32_e32 v16, 1.0, v17
	v_add_f32_e32 v18, -1.0, v16
	v_cndmask_b32_e32 v2, v112, v2, vcc
	v_cmp_ngt_f32_e32 vcc, -1.0, v4
	v_cvt_f32_i32_e32 v12, v12
	s_nop 0
	v_cndmask_b32_e32 v2, v113, v2, vcc
	v_cmp_neq_f32_e32 vcc, -1.0, v4
	s_nop 1
	v_cndmask_b32_e32 v2, v114, v2, vcc
	v_cmp_lt_f32_e64 vcc, |v4|, s84
	s_nop 1
	v_cndmask_b32_e32 v2, v2, v4, vcc
	v_add_f32_e32 v4, -1.0, v17
	v_add_f32_e32 v13, 1.0, v4
	v_sub_f32_e32 v13, v17, v13
	v_sub_f32_e32 v17, v17, v18
	v_add_f32_e32 v13, v3, v13
	v_add_f32_e32 v3, v3, v17
	v_add_f32_e32 v17, v16, v3
	v_rcp_f32_e32 v18, v17
	v_sub_f32_e32 v2, v14, v2
	v_add_f32_e32 v14, v4, v13
	v_sub_f32_e32 v4, v14, v4
	v_sub_f32_e32 v4, v13, v4
	v_sub_f32_e32 v13, v17, v16
	v_sub_f32_e32 v3, v3, v13
	v_mul_f32_e32 v13, v14, v18
	v_mul_f32_e32 v16, v17, v13
	v_fma_f32 v19, v13, v17, -v16
	v_fmac_f32_e32 v19, v13, v3
	v_add_f32_e32 v20, v16, v19
	v_sub_f32_e32 v21, v14, v20
	v_sub_f32_e32 v14, v14, v21
	v_sub_f32_e32 v16, v20, v16
	v_sub_f32_e32 v14, v14, v20
	v_add_f32_e32 v4, v4, v14
	v_sub_f32_e32 v14, v16, v19
	v_add_f32_e32 v4, v14, v4
	v_add_f32_e32 v14, v21, v4
	v_mul_f32_e32 v16, v18, v14
	v_mul_f32_e32 v19, v17, v16
	v_fma_f32 v17, v16, v17, -v19
	v_fmac_f32_e32 v17, v16, v3
	v_sub_f32_e32 v3, v21, v14
	v_add_f32_e32 v3, v4, v3
	v_add_f32_e32 v4, v19, v17
	v_sub_f32_e32 v20, v14, v4
	v_sub_f32_e32 v14, v14, v20
	v_sub_f32_e32 v19, v4, v19
	v_sub_f32_e32 v4, v14, v4
	v_add_f32_e32 v3, v3, v4
	v_sub_f32_e32 v4, v19, v17
	v_add_f32_e32 v3, v4, v3
	v_add_f32_e32 v4, v13, v16
	v_add_f32_e32 v3, v20, v3
	v_sub_f32_e32 v13, v4, v13
	v_mul_f32_e32 v3, v18, v3
	v_sub_f32_e32 v13, v16, v13
	v_add_f32_e32 v3, v13, v3
	v_mul_f32_e32 v17, 0x3f317218, v12
	v_add_f32_e32 v13, v4, v3
	v_fma_f32 v18, v12, s94, -v17
	v_mul_f32_e32 v14, v13, v13
	v_fmac_f32_e32 v18, 0xb102e308, v12
	v_sub_f32_e32 v4, v13, v4
	v_fmamk_f32 v16, v14, 0x3e9b6dac, v83
	v_sub_f32_e32 v3, v3, v4
	v_add_f32_e32 v4, v17, v18
	v_fmaak_f32 v16, v14, v16, 0x3f2aaada
	v_sub_f32_e32 v12, v4, v17
	v_ldexp_f32 v17, v13, 1
	v_mul_f32_e32 v13, v13, v14
	v_mul_f32_e32 v13, v13, v16
	v_add_f32_e32 v14, v17, v13
	v_sub_f32_e32 v16, v14, v17
	v_ldexp_f32 v3, v3, 1
	v_sub_f32_e32 v13, v13, v16
	v_add_f32_e32 v3, v3, v13
	v_add_f32_e32 v13, v14, v3
	v_sub_f32_e32 v14, v13, v14
	v_sub_f32_e32 v3, v3, v14
	v_add_f32_e32 v14, v4, v13
	v_sub_f32_e32 v16, v14, v4
	v_sub_f32_e32 v17, v14, v16
	v_sub_f32_e32 v12, v18, v12
	v_sub_f32_e32 v4, v4, v17
	v_sub_f32_e32 v13, v13, v16
	v_add_f32_e32 v4, v13, v4
	v_add_f32_e32 v13, v12, v3
	v_sub_f32_e32 v16, v13, v12
	v_sub_f32_e32 v17, v13, v16
	v_sub_f32_e32 v12, v12, v17
	v_sub_f32_e32 v3, v3, v16
	v_add_f32_e32 v4, v13, v4
	v_add_f32_e32 v3, v3, v12
	v_add_f32_e32 v12, v14, v4
	v_sub_f32_e32 v13, v12, v14
	v_sub_f32_e32 v4, v4, v13
	v_add_f32_e32 v3, v3, v4
	v_add_f32_e32 v3, v12, v3
	v_cmp_neq_f32_e32 vcc, s95, v11
	s_waitcnt vmcnt(5)
	v_add_f32_e32 v4, v1, v5
	v_mul_f32_e64 v5, |v4|, s92
	v_cndmask_b32_e32 v3, v112, v3, vcc
	v_cmp_ngt_f32_e32 vcc, -1.0, v11
	v_min_f32_e32 v12, 0, v4
	v_add_f32_e32 v2, 0, v2
	v_cndmask_b32_e32 v3, v113, v3, vcc
	v_cmp_neq_f32_e32 vcc, -1.0, v11
	s_nop 1
	v_cndmask_b32_e32 v3, v114, v3, vcc
	v_cmp_lt_f32_e64 vcc, |v11|, s84
	s_nop 1
	v_cndmask_b32_e32 v3, v3, v11, vcc
	v_exp_f32_e32 v11, v5
	v_sub_f32_e32 v3, v15, v3
	v_add_f32_e32 v3, v2, v3
	v_add_f32_e32 v13, 1.0, v11
	v_add_f32_e32 v4, -1.0, v13
	v_sub_f32_e32 v5, v4, v13
	v_add_f32_e32 v5, 1.0, v5
	v_sub_f32_e32 v4, v11, v4
	v_add_f32_e32 v14, v4, v5
	v_frexp_mant_f32_e32 v15, v13
	v_cvt_f64_f32_e32 v[4:5], v13
	v_frexp_exp_i32_f64_e32 v4, v[4:5]
	v_cmp_gt_f32_e32 vcc, s93, v15
	s_nop 1
	v_subbrev_co_u32_e32 v4, vcc, 0, v4, vcc
	v_sub_u32_e32 v5, 0, v4
	v_ldexp_f32 v13, v13, v5
	v_ldexp_f32 v5, v14, v5
	v_add_f32_e32 v14, -1.0, v13
	v_add_f32_e32 v17, 1.0, v13
	v_add_f32_e32 v15, 1.0, v14
	v_add_f32_e32 v18, -1.0, v17
	v_sub_f32_e32 v15, v13, v15
	v_sub_f32_e32 v13, v13, v18
	v_add_f32_e32 v15, v5, v15
	v_add_f32_e32 v5, v5, v13
	v_add_f32_e32 v13, v17, v5
	v_rcp_f32_e32 v18, v13
	v_add_f32_e32 v16, v14, v15
	v_sub_f32_e32 v14, v16, v14
	v_sub_f32_e32 v14, v15, v14
	v_sub_f32_e32 v15, v13, v17
	v_sub_f32_e32 v5, v5, v15
	v_mul_f32_e32 v15, v16, v18
	v_mul_f32_e32 v17, v13, v15
	v_fma_f32 v19, v15, v13, -v17
	v_fmac_f32_e32 v19, v15, v5
	v_add_f32_e32 v20, v17, v19
	v_sub_f32_e32 v21, v16, v20
	v_sub_f32_e32 v16, v16, v21
	v_sub_f32_e32 v17, v20, v17
	v_sub_f32_e32 v16, v16, v20
	v_add_f32_e32 v14, v14, v16
	v_sub_f32_e32 v16, v17, v19
	v_add_f32_e32 v14, v16, v14
	v_add_f32_e32 v16, v21, v14
	v_mul_f32_e32 v17, v18, v16
	v_mul_f32_e32 v19, v13, v17
	v_fma_f32 v13, v17, v13, -v19
	v_fmac_f32_e32 v13, v17, v5
	v_sub_f32_e32 v5, v21, v16
	v_add_f32_e32 v5, v14, v5
	v_add_f32_e32 v14, v19, v13
	v_sub_f32_e32 v20, v16, v14
	v_sub_f32_e32 v16, v16, v20
	v_sub_f32_e32 v19, v14, v19
	v_sub_f32_e32 v14, v16, v14
	v_add_f32_e32 v5, v5, v14
	v_sub_f32_e32 v13, v19, v13
	v_cvt_f32_i32_e32 v4, v4
	v_add_f32_e32 v5, v13, v5
	v_add_f32_e32 v13, v15, v17
	v_add_f32_e32 v5, v20, v5
	v_sub_f32_e32 v14, v13, v15
	v_mul_f32_e32 v5, v18, v5
	v_sub_f32_e32 v14, v17, v14
	v_add_f32_e32 v5, v14, v5
	v_mul_f32_e32 v17, 0x3f317218, v4
	v_add_f32_e32 v14, v13, v5
	v_fma_f32 v18, v4, s94, -v17
	v_mul_f32_e32 v15, v14, v14
	v_fmac_f32_e32 v18, 0xb102e308, v4
	v_sub_f32_e32 v4, v14, v13
	v_fmamk_f32 v16, v15, 0x3e9b6dac, v83
	v_sub_f32_e32 v4, v5, v4
	v_add_f32_e32 v5, v17, v18
	v_fmaak_f32 v16, v15, v16, 0x3f2aaada
	v_sub_f32_e32 v13, v5, v17
	v_ldexp_f32 v17, v14, 1
	v_mul_f32_e32 v14, v14, v15
	v_mul_f32_e32 v14, v14, v16
	v_add_f32_e32 v15, v17, v14
	v_sub_f32_e32 v16, v15, v17
	v_ldexp_f32 v4, v4, 1
	v_sub_f32_e32 v14, v14, v16
	v_add_f32_e32 v4, v4, v14
	v_add_f32_e32 v14, v15, v4
	v_sub_f32_e32 v15, v14, v15
	v_sub_f32_e32 v4, v4, v15
	v_add_f32_e32 v15, v5, v14
	v_sub_f32_e32 v16, v15, v5
	v_sub_f32_e32 v17, v15, v16
	v_sub_f32_e32 v13, v18, v13
	v_sub_f32_e32 v5, v5, v17
	v_sub_f32_e32 v14, v14, v16
	v_add_f32_e32 v5, v14, v5
	v_add_f32_e32 v14, v13, v4
	v_sub_f32_e32 v16, v14, v13
	v_sub_f32_e32 v17, v14, v16
	v_sub_f32_e32 v13, v13, v17
	v_sub_f32_e32 v4, v4, v16
	v_add_f32_e32 v5, v14, v5
	v_add_f32_e32 v4, v4, v13
	v_add_f32_e32 v13, v15, v5
	v_sub_f32_e32 v14, v13, v15
	v_sub_f32_e32 v5, v5, v14
	v_add_f32_e32 v4, v4, v5
	s_waitcnt vmcnt(4)
; DI void fox_cumsum(const Params& P, int bh, unsigned char* smem, int tt) {
;     ...
;     for (int e = 0; e < 8; ++e) {
;         const float xx = gates[((size_t)b * TSEQ + tid * 8 + e) * 16 + 8 + hh] + bf;
;         const float ls = fminf(xx, 0.f) - log1pf(__expf(-fabsf(xx)));
;         run += ls; v[e] = run;
;     }
	v_add_f32_e32 v5, v1, v6
	v_mul_f32_e64 v6, |v5|, s92
	v_add_f32_e32 v4, v13, v4
	v_cmp_neq_f32_e32 vcc, s95, v11
	v_exp_f32_e32 v6, v6
	s_nop 0
	v_cndmask_b32_e32 v4, v112, v4, vcc
	v_cmp_ngt_f32_e32 vcc, -1.0, v11
	v_add_f32_e32 v13, 1.0, v6
	v_frexp_mant_f32_e32 v15, v13
	v_cndmask_b32_e32 v4, v113, v4, vcc
	v_cmp_neq_f32_e32 vcc, -1.0, v11
	s_nop 1
	v_cndmask_b32_e32 v4, v114, v4, vcc
	v_cmp_lt_f32_e64 vcc, |v11|, s84
	s_nop 1
	v_cndmask_b32_e32 v4, v4, v11, vcc
	v_sub_f32_e32 v11, v12, v4
	v_add_f32_e32 v4, -1.0, v13
	v_min_f32_e32 v12, 0, v5
	v_sub_f32_e32 v5, v4, v13
	v_add_f32_e32 v5, 1.0, v5
	v_sub_f32_e32 v4, v6, v4
	v_add_f32_e32 v14, v4, v5
	v_cvt_f64_f32_e32 v[4:5], v13
	v_frexp_exp_i32_f64_e32 v4, v[4:5]
	v_cmp_gt_f32_e32 vcc, s93, v15
	s_nop 1
	v_subbrev_co_u32_e32 v4, vcc, 0, v4, vcc
	v_sub_u32_e32 v5, 0, v4
	v_ldexp_f32 v13, v13, v5
	v_ldexp_f32 v5, v14, v5
	v_add_f32_e32 v14, -1.0, v13
	v_add_f32_e32 v17, 1.0, v13
	v_add_f32_e32 v15, 1.0, v14
	v_add_f32_e32 v18, -1.0, v17
	v_sub_f32_e32 v15, v13, v15
	v_sub_f32_e32 v13, v13, v18
	v_add_f32_e32 v15, v5, v15
	v_add_f32_e32 v5, v5, v13
	v_add_f32_e32 v13, v17, v5
	v_rcp_f32_e32 v18, v13
	v_add_f32_e32 v16, v14, v15
	v_sub_f32_e32 v14, v16, v14
	v_sub_f32_e32 v14, v15, v14
	v_sub_f32_e32 v15, v13, v17
	v_sub_f32_e32 v5, v5, v15
	v_mul_f32_e32 v15, v16, v18
	v_mul_f32_e32 v17, v13, v15
	v_fma_f32 v19, v15, v13, -v17
	v_fmac_f32_e32 v19, v15, v5
	v_add_f32_e32 v20, v17, v19
	v_sub_f32_e32 v21, v16, v20
	v_sub_f32_e32 v16, v16, v21
	v_sub_f32_e32 v17, v20, v17
	v_sub_f32_e32 v16, v16, v20
	v_add_f32_e32 v14, v14, v16
	v_sub_f32_e32 v16, v17, v19
	v_add_f32_e32 v14, v16, v14
	v_add_f32_e32 v16, v21, v14
	v_mul_f32_e32 v17, v18, v16
	v_mul_f32_e32 v19, v13, v17
	v_fma_f32 v13, v17, v13, -v19
	v_fmac_f32_e32 v13, v17, v5
	v_sub_f32_e32 v5, v21, v16
	v_add_f32_e32 v5, v14, v5
	v_add_f32_e32 v14, v19, v13
	v_sub_f32_e32 v20, v16, v14
	v_sub_f32_e32 v16, v16, v20
	v_sub_f32_e32 v19, v14, v19
	v_sub_f32_e32 v14, v16, v14
	v_add_f32_e32 v5, v5, v14
	v_sub_f32_e32 v13, v19, v13
	v_cvt_f32_i32_e32 v4, v4
	v_add_f32_e32 v5, v13, v5
	v_add_f32_e32 v13, v15, v17
	v_add_f32_e32 v5, v20, v5
	v_sub_f32_e32 v14, v13, v15
	v_mul_f32_e32 v5, v18, v5
	v_sub_f32_e32 v14, v17, v14
	v_add_f32_e32 v5, v14, v5
	v_mul_f32_e32 v17, 0x3f317218, v4
	v_add_f32_e32 v14, v13, v5
	v_fma_f32 v18, v4, s94, -v17
	v_mul_f32_e32 v15, v14, v14
	v_fmac_f32_e32 v18, 0xb102e308, v4
	v_sub_f32_e32 v4, v14, v13
	v_fmamk_f32 v16, v15, 0x3e9b6dac, v83
	v_sub_f32_e32 v4, v5, v4
	v_add_f32_e32 v5, v17, v18
	v_fmaak_f32 v16, v15, v16, 0x3f2aaada
	v_sub_f32_e32 v13, v5, v17
	v_ldexp_f32 v17, v14, 1
	v_mul_f32_e32 v14, v14, v15
	v_mul_f32_e32 v14, v14, v16
	v_add_f32_e32 v15, v17, v14
	v_sub_f32_e32 v16, v15, v17
	v_ldexp_f32 v4, v4, 1
	v_sub_f32_e32 v14, v14, v16
	v_add_f32_e32 v4, v4, v14
	v_add_f32_e32 v14, v15, v4
	v_sub_f32_e32 v15, v14, v15
	v_sub_f32_e32 v4, v4, v15
	v_add_f32_e32 v15, v5, v14
	v_sub_f32_e32 v16, v15, v5
	v_sub_f32_e32 v17, v15, v16
	v_sub_f32_e32 v13, v18, v13
	v_sub_f32_e32 v5, v5, v17
	v_sub_f32_e32 v14, v14, v16
	v_add_f32_e32 v5, v14, v5
	v_add_f32_e32 v14, v13, v4
	v_sub_f32_e32 v16, v14, v13
	v_sub_f32_e32 v17, v14, v16
	v_sub_f32_e32 v13, v13, v17
	v_sub_f32_e32 v4, v4, v16
	v_add_f32_e32 v5, v14, v5
	v_add_f32_e32 v4, v4, v13
	v_add_f32_e32 v13, v15, v5
	v_sub_f32_e32 v14, v13, v15
	v_sub_f32_e32 v5, v5, v14
	v_add_f32_e32 v4, v4, v5
	v_add_f32_e32 v4, v13, v4
	v_cmp_neq_f32_e32 vcc, s95, v6
	s_nop 1
	v_cndmask_b32_e32 v4, v112, v4, vcc
	v_cmp_ngt_f32_e32 vcc, -1.0, v6
	s_nop 1
	v_cndmask_b32_e32 v4, v113, v4, vcc
	v_cmp_neq_f32_e32 vcc, -1.0, v6
	s_nop 1
	v_cndmask_b32_e32 v4, v114, v4, vcc
	v_cmp_lt_f32_e64 vcc, |v6|, s84
	s_nop 1
	v_cndmask_b32_e32 v4, v4, v6, vcc
	s_waitcnt vmcnt(3)
	v_add_f32_e32 v6, v1, v7
	v_sub_f32_e32 v5, v12, v4
	v_mul_f32_e64 v4, |v6|, s92
	v_exp_f32_e32 v12, v4
	v_add_f32_e32 v4, v3, v11
	v_min_f32_e32 v11, 0, v6
	v_add_f32_e32 v5, v4, v5
	v_add_f32_e32 v13, 1.0, v12
	v_add_f32_e32 v6, -1.0, v13
	v_sub_f32_e32 v7, v6, v13
	v_add_f32_e32 v7, 1.0, v7
	v_sub_f32_e32 v6, v12, v6
	v_add_f32_e32 v14, v6, v7
	v_frexp_mant_f32_e32 v15, v13
	v_cvt_f64_f32_e32 v[6:7], v13
	v_frexp_exp_i32_f64_e32 v6, v[6:7]
	v_cmp_gt_f32_e32 vcc, s93, v15
	s_nop 1
	v_subbrev_co_u32_e32 v6, vcc, 0, v6, vcc
	v_sub_u32_e32 v7, 0, v6
	v_ldexp_f32 v13, v13, v7
	v_ldexp_f32 v7, v14, v7
	v_add_f32_e32 v14, -1.0, v13
	v_add_f32_e32 v17, 1.0, v13
	v_add_f32_e32 v15, 1.0, v14
	v_add_f32_e32 v18, -1.0, v17
	v_sub_f32_e32 v15, v13, v15
	v_sub_f32_e32 v13, v13, v18
	v_add_f32_e32 v15, v7, v15
	v_add_f32_e32 v7, v7, v13
	v_add_f32_e32 v13, v17, v7
	v_rcp_f32_e32 v18, v13
	v_add_f32_e32 v16, v14, v15
	v_sub_f32_e32 v14, v16, v14
	v_sub_f32_e32 v14, v15, v14
	v_sub_f32_e32 v15, v13, v17
	v_sub_f32_e32 v7, v7, v15
	v_mul_f32_e32 v15, v16, v18
	v_mul_f32_e32 v17, v13, v15
	v_fma_f32 v19, v15, v13, -v17
	v_fmac_f32_e32 v19, v15, v7
	v_add_f32_e32 v20, v17, v19
	v_sub_f32_e32 v21, v16, v20
	v_sub_f32_e32 v16, v16, v21
	v_sub_f32_e32 v17, v20, v17
	v_sub_f32_e32 v16, v16, v20
	v_add_f32_e32 v14, v14, v16
	v_sub_f32_e32 v16, v17, v19
	v_add_f32_e32 v14, v16, v14
	v_add_f32_e32 v16, v21, v14
	v_mul_f32_e32 v17, v18, v16
	v_mul_f32_e32 v19, v13, v17
	v_fma_f32 v13, v17, v13, -v19
	v_fmac_f32_e32 v13, v17, v7
	v_sub_f32_e32 v7, v21, v16
	v_add_f32_e32 v7, v14, v7
	v_add_f32_e32 v14, v19, v13
	v_sub_f32_e32 v20, v16, v14
	v_sub_f32_e32 v16, v16, v20
	v_sub_f32_e32 v19, v14, v19
	v_sub_f32_e32 v14, v16, v14
	v_add_f32_e32 v7, v7, v14
	v_sub_f32_e32 v13, v19, v13
	v_cvt_f32_i32_e32 v6, v6
	v_add_f32_e32 v7, v13, v7
	v_add_f32_e32 v13, v15, v17
	v_add_f32_e32 v7, v20, v7
	v_sub_f32_e32 v14, v13, v15
	v_mul_f32_e32 v7, v18, v7
	v_sub_f32_e32 v14, v17, v14
	v_add_f32_e32 v7, v14, v7
	v_mul_f32_e32 v17, 0x3f317218, v6
	v_add_f32_e32 v14, v13, v7
	v_fma_f32 v18, v6, s94, -v17
	v_mul_f32_e32 v15, v14, v14
	v_fmac_f32_e32 v18, 0xb102e308, v6
	v_sub_f32_e32 v6, v14, v13
	v_fmamk_f32 v16, v15, 0x3e9b6dac, v83
	v_sub_f32_e32 v6, v7, v6
	v_add_f32_e32 v7, v17, v18
	v_fmaak_f32 v16, v15, v16, 0x3f2aaada
	v_sub_f32_e32 v13, v7, v17
	v_ldexp_f32 v17, v14, 1
	v_mul_f32_e32 v14, v14, v15
	v_mul_f32_e32 v14, v14, v16
	v_add_f32_e32 v15, v17, v14
	v_sub_f32_e32 v16, v15, v17
	v_ldexp_f32 v6, v6, 1
	v_sub_f32_e32 v14, v14, v16
	v_add_f32_e32 v6, v6, v14
	v_add_f32_e32 v14, v15, v6
	v_sub_f32_e32 v15, v14, v15
	v_sub_f32_e32 v6, v6, v15
	v_add_f32_e32 v15, v7, v14
	v_sub_f32_e32 v16, v15, v7
	v_sub_f32_e32 v17, v15, v16
	v_sub_f32_e32 v13, v18, v13
	v_sub_f32_e32 v7, v7, v17
	v_sub_f32_e32 v14, v14, v16
	v_add_f32_e32 v7, v14, v7
	v_add_f32_e32 v14, v13, v6
	v_sub_f32_e32 v16, v14, v13
	v_sub_f32_e32 v17, v14, v16
	v_sub_f32_e32 v13, v13, v17
	v_sub_f32_e32 v6, v6, v16
	v_add_f32_e32 v7, v14, v7
	v_add_f32_e32 v6, v6, v13
	v_add_f32_e32 v13, v15, v7
	v_sub_f32_e32 v14, v13, v15
	v_sub_f32_e32 v7, v7, v14
	v_add_f32_e32 v6, v6, v7
	s_waitcnt vmcnt(2)
; DI void fox_cumsum(const Params& P, int bh, unsigned char* smem, int tt) {
;     ...
;     for (int e = 0; e < 8; ++e) {
;         const float xx = gates[((size_t)b * TSEQ + tid * 8 + e) * 16 + 8 + hh] + bf;
;         const float ls = fminf(xx, 0.f) - log1pf(__expf(-fabsf(xx)));
;         run += ls; v[e] = run;
;     }
	v_add_f32_e32 v7, v1, v8
	v_mul_f32_e64 v8, |v7|, s92
	v_add_f32_e32 v6, v13, v6
	v_cmp_neq_f32_e32 vcc, s95, v12
	v_exp_f32_e32 v8, v8
	s_nop 0
	v_cndmask_b32_e32 v6, v112, v6, vcc
	v_cmp_ngt_f32_e32 vcc, -1.0, v12
	v_add_f32_e32 v13, 1.0, v8
	v_frexp_mant_f32_e32 v15, v13
	v_cndmask_b32_e32 v6, v113, v6, vcc
	v_cmp_neq_f32_e32 vcc, -1.0, v12
	s_nop 1
	v_cndmask_b32_e32 v6, v114, v6, vcc
	v_cmp_lt_f32_e64 vcc, |v12|, s84
	s_nop 1
	v_cndmask_b32_e32 v6, v6, v12, vcc
	v_sub_f32_e32 v11, v11, v6
	v_add_f32_e32 v6, -1.0, v13
	v_min_f32_e32 v12, 0, v7
	v_sub_f32_e32 v7, v6, v13
	v_add_f32_e32 v7, 1.0, v7
	v_sub_f32_e32 v6, v8, v6
	v_add_f32_e32 v14, v6, v7
	v_cvt_f64_f32_e32 v[6:7], v13
	v_frexp_exp_i32_f64_e32 v6, v[6:7]
	v_cmp_gt_f32_e32 vcc, s93, v15
	s_nop 1
	v_subbrev_co_u32_e32 v6, vcc, 0, v6, vcc
	v_sub_u32_e32 v7, 0, v6
	v_ldexp_f32 v13, v13, v7
	v_ldexp_f32 v7, v14, v7
	v_add_f32_e32 v14, -1.0, v13
	v_add_f32_e32 v17, 1.0, v13
	v_add_f32_e32 v15, 1.0, v14
	v_add_f32_e32 v18, -1.0, v17
	v_sub_f32_e32 v15, v13, v15
	v_sub_f32_e32 v13, v13, v18
	v_add_f32_e32 v15, v7, v15
	v_add_f32_e32 v7, v7, v13
	v_add_f32_e32 v13, v17, v7
	v_rcp_f32_e32 v18, v13
	v_add_f32_e32 v16, v14, v15
	v_sub_f32_e32 v14, v16, v14
	v_sub_f32_e32 v14, v15, v14
	v_sub_f32_e32 v15, v13, v17
	v_sub_f32_e32 v7, v7, v15
	v_mul_f32_e32 v15, v16, v18
	v_mul_f32_e32 v17, v13, v15
	v_fma_f32 v19, v15, v13, -v17
	v_fmac_f32_e32 v19, v15, v7
	v_add_f32_e32 v20, v17, v19
	v_sub_f32_e32 v21, v16, v20
	v_sub_f32_e32 v16, v16, v21
	v_sub_f32_e32 v17, v20, v17
	v_sub_f32_e32 v16, v16, v20
	v_add_f32_e32 v14, v14, v16
	v_sub_f32_e32 v16, v17, v19
	v_add_f32_e32 v14, v16, v14
	v_add_f32_e32 v16, v21, v14
	v_mul_f32_e32 v17, v18, v16
	v_mul_f32_e32 v19, v13, v17
	v_fma_f32 v13, v17, v13, -v19
	v_fmac_f32_e32 v13, v17, v7
	v_sub_f32_e32 v7, v21, v16
	v_add_f32_e32 v7, v14, v7
	v_add_f32_e32 v14, v19, v13
	v_sub_f32_e32 v20, v16, v14
	v_sub_f32_e32 v16, v16, v20
	v_sub_f32_e32 v19, v14, v19
	v_sub_f32_e32 v14, v16, v14
	v_add_f32_e32 v7, v7, v14
	v_sub_f32_e32 v13, v19, v13
	v_cvt_f32_i32_e32 v6, v6
	v_add_f32_e32 v7, v13, v7
	v_add_f32_e32 v13, v15, v17
	v_add_f32_e32 v7, v20, v7
	v_sub_f32_e32 v14, v13, v15
	v_mul_f32_e32 v7, v18, v7
	v_sub_f32_e32 v14, v17, v14
	v_add_f32_e32 v7, v14, v7
	v_mul_f32_e32 v17, 0x3f317218, v6
	v_add_f32_e32 v14, v13, v7
	v_fma_f32 v18, v6, s94, -v17
	v_mul_f32_e32 v15, v14, v14
	v_fmac_f32_e32 v18, 0xb102e308, v6
	v_sub_f32_e32 v6, v14, v13
	v_fmamk_f32 v16, v15, 0x3e9b6dac, v83
	v_sub_f32_e32 v6, v7, v6
	v_add_f32_e32 v7, v17, v18
	v_fmaak_f32 v16, v15, v16, 0x3f2aaada
	v_sub_f32_e32 v13, v7, v17
	v_ldexp_f32 v17, v14, 1
	v_mul_f32_e32 v14, v14, v15
	v_mul_f32_e32 v14, v14, v16
	v_add_f32_e32 v15, v17, v14
	v_sub_f32_e32 v16, v15, v17
	v_ldexp_f32 v6, v6, 1
	v_sub_f32_e32 v14, v14, v16
	v_add_f32_e32 v6, v6, v14
	v_add_f32_e32 v14, v15, v6
	v_sub_f32_e32 v15, v14, v15
	v_sub_f32_e32 v6, v6, v15
	v_add_f32_e32 v15, v7, v14
	v_sub_f32_e32 v16, v15, v7
	v_sub_f32_e32 v17, v15, v16
	v_sub_f32_e32 v13, v18, v13
	v_sub_f32_e32 v7, v7, v17
	v_sub_f32_e32 v14, v14, v16
	v_add_f32_e32 v7, v14, v7
	v_add_f32_e32 v14, v13, v6
	v_sub_f32_e32 v16, v14, v13
	v_sub_f32_e32 v17, v14, v16
	v_sub_f32_e32 v13, v13, v17
	v_sub_f32_e32 v6, v6, v16
	v_add_f32_e32 v7, v14, v7
	v_add_f32_e32 v6, v6, v13
	v_add_f32_e32 v13, v15, v7
	v_sub_f32_e32 v14, v13, v15
	v_sub_f32_e32 v7, v7, v14
	v_add_f32_e32 v6, v6, v7
	v_add_f32_e32 v6, v13, v6
	v_cmp_neq_f32_e32 vcc, s95, v8
	s_nop 1
	v_cndmask_b32_e32 v6, v112, v6, vcc
	v_cmp_ngt_f32_e32 vcc, -1.0, v8
	s_nop 1
	v_cndmask_b32_e32 v6, v113, v6, vcc
	v_cmp_neq_f32_e32 vcc, -1.0, v8
	s_nop 1
	v_cndmask_b32_e32 v6, v114, v6, vcc
	v_cmp_lt_f32_e64 vcc, |v8|, s84
	s_nop 1
	v_cndmask_b32_e32 v6, v6, v8, vcc
	s_waitcnt vmcnt(1)
	v_add_f32_e32 v8, v1, v9
	v_sub_f32_e32 v7, v12, v6
	v_mul_f32_e64 v6, |v8|, s92
	v_exp_f32_e32 v12, v6
	v_add_f32_e32 v6, v5, v11
	v_min_f32_e32 v11, 0, v8
	s_waitcnt vmcnt(0)
	v_add_f32_e32 v1, v1, v10
	v_add_f32_e32 v13, 1.0, v12
	v_add_f32_e32 v8, -1.0, v13
	v_sub_f32_e32 v9, v8, v13
	v_add_f32_e32 v9, 1.0, v9
	v_sub_f32_e32 v8, v12, v8
	v_add_f32_e32 v14, v8, v9
	v_frexp_mant_f32_e32 v15, v13
	v_cvt_f64_f32_e32 v[8:9], v13
	v_frexp_exp_i32_f64_e32 v8, v[8:9]
	v_cmp_gt_f32_e32 vcc, s93, v15
	v_add_f32_e32 v7, v6, v7
	s_nop 0
	v_subbrev_co_u32_e32 v8, vcc, 0, v8, vcc
	v_sub_u32_e32 v9, 0, v8
	v_ldexp_f32 v13, v13, v9
	v_ldexp_f32 v9, v14, v9
	v_add_f32_e32 v14, -1.0, v13
	v_add_f32_e32 v17, 1.0, v13
	v_add_f32_e32 v15, 1.0, v14
	v_add_f32_e32 v18, -1.0, v17
	v_sub_f32_e32 v15, v13, v15
	v_sub_f32_e32 v13, v13, v18
	v_add_f32_e32 v15, v9, v15
	v_add_f32_e32 v9, v9, v13
	v_add_f32_e32 v13, v17, v9
	v_rcp_f32_e32 v18, v13
	v_add_f32_e32 v16, v14, v15
	v_sub_f32_e32 v14, v16, v14
	v_sub_f32_e32 v14, v15, v14
	v_sub_f32_e32 v15, v13, v17
	v_sub_f32_e32 v9, v9, v15
	v_mul_f32_e32 v15, v16, v18
	v_mul_f32_e32 v17, v13, v15
	v_fma_f32 v19, v15, v13, -v17
	v_fmac_f32_e32 v19, v15, v9
	v_add_f32_e32 v20, v17, v19
	v_sub_f32_e32 v21, v16, v20
	v_sub_f32_e32 v16, v16, v21
	v_sub_f32_e32 v17, v20, v17
	v_sub_f32_e32 v16, v16, v20
	v_add_f32_e32 v14, v14, v16
	v_sub_f32_e32 v16, v17, v19
	v_add_f32_e32 v14, v16, v14
	v_add_f32_e32 v16, v21, v14
	v_mul_f32_e32 v17, v18, v16
	v_mul_f32_e32 v19, v13, v17
	v_fma_f32 v13, v17, v13, -v19
	v_fmac_f32_e32 v13, v17, v9
	v_sub_f32_e32 v9, v21, v16
	v_add_f32_e32 v9, v14, v9
	v_add_f32_e32 v14, v19, v13
	v_sub_f32_e32 v20, v16, v14
	v_sub_f32_e32 v16, v16, v20
	v_sub_f32_e32 v19, v14, v19
	v_sub_f32_e32 v14, v16, v14
	v_add_f32_e32 v9, v9, v14
	v_sub_f32_e32 v13, v19, v13
; DI float shup(float v, int o, int lane) { return __int_as_float(__builtin_amdgcn_ds_bpermute(((lane - o) & 63) << 2, __float_as_int(v))); }
; DI void fox_cumsum(const Params& P, int bh, unsigned char* smem, int tt) {
;     ...
;     for (int e = 0; e < 8; ++e) {
;         const float xx = gates[((size_t)b * TSEQ + tid * 8 + e) * 16 + 8 + hh] + bf;
;         const float ls = fminf(xx, 0.f) - log1pf(__expf(-fabsf(xx)));
;         run += ls; v[e] = run;
;     }
;     float sc = run;
; #pragma unroll
;     for (int o = 1; o < 64; o <<= 1) { const float t = shup(sc, o, lane); if (lane >= o) sc += t; }
;     if (lane == 63) wsum[wave] = sc;
;     __syncthreads();
;     float off = sc - run;
;     for (int w = 0; w < wave; ++w) off += wsum[w];
	v_cvt_f32_i32_e32 v8, v8
	v_add_f32_e32 v9, v13, v9
	v_add_f32_e32 v13, v15, v17
	v_add_f32_e32 v9, v20, v9
	v_sub_f32_e32 v14, v13, v15
	v_mul_f32_e32 v9, v18, v9
	v_sub_f32_e32 v14, v17, v14
	v_add_f32_e32 v9, v14, v9
	v_mul_f32_e32 v17, 0x3f317218, v8
	v_add_f32_e32 v14, v13, v9
	v_fma_f32 v18, v8, s94, -v17
	v_mul_f32_e32 v15, v14, v14
	v_fmac_f32_e32 v18, 0xb102e308, v8
	v_sub_f32_e32 v8, v14, v13
	v_fmamk_f32 v16, v15, 0x3e9b6dac, v83
	v_sub_f32_e32 v8, v9, v8
	v_add_f32_e32 v9, v17, v18
	v_fmaak_f32 v16, v15, v16, 0x3f2aaada
	v_sub_f32_e32 v13, v9, v17
	v_ldexp_f32 v17, v14, 1
	v_mul_f32_e32 v14, v14, v15
	v_mul_f32_e32 v14, v14, v16
	v_add_f32_e32 v15, v17, v14
	v_sub_f32_e32 v16, v15, v17
	v_ldexp_f32 v8, v8, 1
	v_sub_f32_e32 v14, v14, v16
	v_add_f32_e32 v8, v8, v14
	v_add_f32_e32 v14, v15, v8
	v_sub_f32_e32 v15, v14, v15
	v_sub_f32_e32 v8, v8, v15
	v_add_f32_e32 v15, v9, v14
	v_sub_f32_e32 v16, v15, v9
	v_sub_f32_e32 v17, v15, v16
	v_sub_f32_e32 v13, v18, v13
	v_sub_f32_e32 v9, v9, v17
	v_sub_f32_e32 v14, v14, v16
	v_add_f32_e32 v9, v14, v9
	v_add_f32_e32 v14, v13, v8
	v_sub_f32_e32 v16, v14, v13
	v_sub_f32_e32 v17, v14, v16
	v_sub_f32_e32 v13, v13, v17
	v_sub_f32_e32 v8, v8, v16
	v_add_f32_e32 v9, v14, v9
	v_add_f32_e32 v8, v8, v13
	v_add_f32_e32 v13, v15, v9
	v_sub_f32_e32 v14, v13, v15
	v_sub_f32_e32 v9, v9, v14
	v_add_f32_e32 v8, v8, v9
	v_mul_f32_e64 v9, |v1|, s92
	v_add_f32_e32 v8, v13, v8
	v_cmp_neq_f32_e32 vcc, s95, v12
	v_exp_f32_e32 v10, v9
	v_min_f32_e32 v1, 0, v1
	v_cndmask_b32_e32 v8, v112, v8, vcc
	v_cmp_ngt_f32_e32 vcc, -1.0, v12
	s_nop 1
	v_cndmask_b32_e32 v8, v113, v8, vcc
	v_cmp_neq_f32_e32 vcc, -1.0, v12
	s_nop 1
	v_cndmask_b32_e32 v8, v114, v8, vcc
	v_cmp_lt_f32_e64 vcc, |v12|, s84
	s_nop 1
	v_cndmask_b32_e32 v8, v8, v12, vcc
	v_add_f32_e32 v12, 1.0, v10
	v_sub_f32_e32 v11, v11, v8
	v_add_f32_e32 v8, -1.0, v12
	v_sub_f32_e32 v9, v8, v12
	v_add_f32_e32 v9, 1.0, v9
	v_sub_f32_e32 v8, v10, v8
	v_add_f32_e32 v13, v8, v9
	v_frexp_mant_f32_e32 v14, v12
	v_cvt_f64_f32_e32 v[8:9], v12
	v_frexp_exp_i32_f64_e32 v8, v[8:9]
	v_cmp_gt_f32_e32 vcc, s93, v14
	s_nop 1
	v_subbrev_co_u32_e32 v8, vcc, 0, v8, vcc
	v_sub_u32_e32 v9, 0, v8
	v_ldexp_f32 v12, v12, v9
	v_ldexp_f32 v9, v13, v9
	v_add_f32_e32 v13, -1.0, v12
	v_add_f32_e32 v16, 1.0, v12
	v_add_f32_e32 v14, 1.0, v13
	v_add_f32_e32 v17, -1.0, v16
	v_sub_f32_e32 v14, v12, v14
	v_sub_f32_e32 v12, v12, v17
	v_add_f32_e32 v14, v9, v14
	v_add_f32_e32 v9, v9, v12
	v_add_f32_e32 v12, v16, v9
	v_rcp_f32_e32 v17, v12
	v_add_f32_e32 v15, v13, v14
	v_sub_f32_e32 v13, v15, v13
	v_sub_f32_e32 v13, v14, v13
	v_sub_f32_e32 v14, v12, v16
	v_sub_f32_e32 v9, v9, v14
	v_mul_f32_e32 v14, v15, v17
	v_mul_f32_e32 v16, v12, v14
	v_fma_f32 v18, v14, v12, -v16
	v_fmac_f32_e32 v18, v14, v9
	v_add_f32_e32 v19, v16, v18
	v_sub_f32_e32 v20, v15, v19
	v_sub_f32_e32 v15, v15, v20
	v_sub_f32_e32 v16, v19, v16
	v_sub_f32_e32 v15, v15, v19
	v_add_f32_e32 v13, v13, v15
	v_sub_f32_e32 v15, v16, v18
	v_add_f32_e32 v13, v15, v13
	v_add_f32_e32 v15, v20, v13
	v_mul_f32_e32 v16, v17, v15
	v_mul_f32_e32 v18, v12, v16
	v_fma_f32 v12, v16, v12, -v18
	v_fmac_f32_e32 v12, v16, v9
	v_sub_f32_e32 v9, v20, v15
	v_add_f32_e32 v9, v13, v9
	v_add_f32_e32 v13, v18, v12
	v_sub_f32_e32 v19, v15, v13
	v_sub_f32_e32 v15, v15, v19
	v_sub_f32_e32 v18, v13, v18
	v_sub_f32_e32 v13, v15, v13
	v_add_f32_e32 v9, v9, v13
	v_sub_f32_e32 v12, v18, v12
	v_cvt_f32_i32_e32 v8, v8
	v_add_f32_e32 v9, v12, v9
	v_add_f32_e32 v12, v14, v16
	v_add_f32_e32 v9, v19, v9
	v_sub_f32_e32 v13, v12, v14
	v_mul_f32_e32 v9, v17, v9
	v_sub_f32_e32 v13, v16, v13
	v_add_f32_e32 v9, v13, v9
	v_mul_f32_e32 v16, 0x3f317218, v8
	v_add_f32_e32 v13, v12, v9
	v_fma_f32 v17, v8, s94, -v16
	v_mul_f32_e32 v14, v13, v13
	v_fmac_f32_e32 v17, 0xb102e308, v8
	v_sub_f32_e32 v8, v13, v12
	v_fmamk_f32 v15, v14, 0x3e9b6dac, v83
	v_sub_f32_e32 v8, v9, v8
	v_add_f32_e32 v9, v16, v17
	v_fmaak_f32 v15, v14, v15, 0x3f2aaada
	v_sub_f32_e32 v12, v9, v16
	v_ldexp_f32 v16, v13, 1
	v_mul_f32_e32 v13, v13, v14
	v_mul_f32_e32 v13, v13, v15
	v_add_f32_e32 v14, v16, v13
	v_sub_f32_e32 v15, v14, v16
	v_ldexp_f32 v8, v8, 1
	v_sub_f32_e32 v13, v13, v15
	v_add_f32_e32 v8, v8, v13
	v_add_f32_e32 v13, v14, v8
	v_sub_f32_e32 v14, v13, v14
	v_sub_f32_e32 v8, v8, v14
	v_add_f32_e32 v14, v9, v13
	v_sub_f32_e32 v15, v14, v9
	v_sub_f32_e32 v16, v14, v15
	v_sub_f32_e32 v12, v17, v12
	v_sub_f32_e32 v9, v9, v16
	v_sub_f32_e32 v13, v13, v15
	v_add_f32_e32 v9, v13, v9
	v_add_f32_e32 v13, v12, v8
	v_sub_f32_e32 v15, v13, v12
	v_sub_f32_e32 v16, v13, v15
	v_sub_f32_e32 v12, v12, v16
	v_sub_f32_e32 v8, v8, v15
	v_add_f32_e32 v9, v13, v9
	v_add_f32_e32 v8, v8, v12
	v_add_f32_e32 v12, v14, v9
	v_sub_f32_e32 v13, v12, v14
	v_sub_f32_e32 v9, v9, v13
	v_add_f32_e32 v8, v8, v9
	v_add_f32_e32 v8, v12, v8
	v_cmp_neq_f32_e32 vcc, s95, v10
	s_nop 1
	v_cndmask_b32_e32 v8, v112, v8, vcc
	v_cmp_ngt_f32_e32 vcc, -1.0, v10
	s_nop 1
	v_cndmask_b32_e32 v8, v113, v8, vcc
	v_cmp_neq_f32_e32 vcc, -1.0, v10
	s_nop 1
	v_cndmask_b32_e32 v8, v114, v8, vcc
	v_cmp_lt_f32_e64 vcc, |v10|, s84
	s_nop 1
	v_cndmask_b32_e32 v8, v8, v10, vcc
	v_sub_f32_e32 v1, v1, v8
	v_add_f32_e32 v8, v7, v11
	v_add_f32_e32 v9, v8, v1
	v_lshlrev_b32_e32 v1, 2, v124
	v_add_u32_e32 v10, 0xfc, v1
	v_and_b32_e32 v10, 0xfc, v10
	ds_bpermute_b32 v10, v10, v9
	v_cmp_eq_u32_e32 vcc, 0, v123
	v_add_u32_e32 v11, 0xf8, v1
	v_and_b32_e32 v11, 0xfc, v11
	s_waitcnt lgkmcnt(0)
	v_add_f32_e32 v10, v9, v10
	v_cndmask_b32_e32 v10, v10, v9, vcc
	ds_bpermute_b32 v11, v11, v10
	v_cmp_gt_u32_e32 vcc, 2, v123
	s_waitcnt lgkmcnt(0)
	v_add_f32_e32 v11, v10, v11
	v_cndmask_b32_e32 v10, v11, v10, vcc
	v_add_u32_e32 v11, 0xf0, v1
	v_and_b32_e32 v11, 0xfc, v11
	ds_bpermute_b32 v11, v11, v10
	v_cmp_gt_u32_e32 vcc, 4, v123
	s_waitcnt lgkmcnt(0)
	v_add_f32_e32 v11, v10, v11
	v_cndmask_b32_e32 v10, v11, v10, vcc
	v_add_u32_e32 v11, 0xe0, v1
	v_and_b32_e32 v11, 0xfc, v11
	ds_bpermute_b32 v11, v11, v10
	v_cmp_gt_u32_e32 vcc, 8, v123
	s_waitcnt lgkmcnt(0)
	v_add_f32_e32 v11, v10, v11
	v_cndmask_b32_e32 v10, v11, v10, vcc
	v_add_u32_e32 v11, 0xc0, v1
	v_and_b32_e32 v11, 0xfc, v11
	ds_bpermute_b32 v11, v11, v10
	v_cmp_gt_u32_e32 vcc, 16, v123
	v_bitop3_b32 v1, v1, s2, v115 bitop3:0x6c
	s_waitcnt lgkmcnt(0)
	v_add_f32_e32 v11, v10, v11
	v_cndmask_b32_e32 v10, v11, v10, vcc
	ds_bpermute_b32 v1, v1, v10
	v_cmp_eq_u32_e32 vcc, 63, v123
	s_waitcnt lgkmcnt(0)
	v_add_f32_e32 v11, v10, v1
	v_lshrrev_b32_e32 v1, 6, v124
	s_and_saveexec_b64 s[2:3], vcc
	v_lshl_add_u32 v12, v1, 2, v125
	ds_write_b32 v12, v11
	s_or_b64 exec, exec, s[2:3]
	v_cmp_gt_u32_e32 vcc, 32, v123
	s_waitcnt lgkmcnt(0)
	s_barrier
	v_cndmask_b32_e32 v10, v11, v10, vcc
	v_sub_f32_e32 v10, v10, v9
	v_cmp_lt_u32_e32 vcc, 63, v124
	s_and_saveexec_b64 s[2:3], vcc
	s_cbranch_execz .LBB0_227
	v_lshlrev_b32_e32 v1, 2, v1
	s_mov_b64 s[4:5], 0

; DI int fresh_tid(int wid_s) { int l; asm volatile("v_mbcnt_lo_u32_b32 %0, -1, 0\n\tv_mbcnt_hi_u32_b32 %0, -1, %0" : "=v"(l)); return wid_s * 64 + l; }
; DI unsigned xb_ld(unsigned* p)              { return __hip_atomic_load(p, __ATOMIC_RELAXED, __HIP_MEMORY_SCOPE_AGENT); }
; DI unsigned xb_add(unsigned* p, unsigned v) { return __hip_atomic_fetch_add(p, v, __ATOMIC_RELAXED, __HIP_MEMORY_SCOPE_AGENT); }
; #define XB_SPIN(cond, bar) do { unsigned _sp = 0; while (cond) { __builtin_amdgcn_s_sleep(1); \
;     if ((++_sp & 255u) == 0u) { if (xb_ld(&(bar)[XB_TMO])) break; if (_sp > XB_SPIN_CAP) { atomicAdd(&(bar)[XB_TMO], 1u); break; } } } } while (0)
; DI void xcd_barrier(const XcdBarrier& b, const int wid_s) {
;     asm volatile("s_waitcnt vmcnt(0)" ::: "memory");
;     __syncthreads();
;     if (fresh_tid(wid_s) == 0) {
;         unsigned* bar = b.bar;
;         __builtin_amdgcn_s_waitcnt(0);
;         unsigned nloc = b.st[0], nx = b.st[1];
;         if (nloc == 0u) { xcd_barrier_complete(bar, b.x, nloc, nx); b.st[0] = nloc; b.st[1] = nx; }
;         const unsigned old = xb_add(&bar[XB_XSUB(b.x)], 1u);
;         const unsigned gen = old / nloc;
;         if (old + 1u == (gen + 1u) * nloc) {
;             __builtin_amdgcn_fence(__ATOMIC_RELEASE, "agent");
;             asm volatile("s_waitcnt vmcnt(0)" ::: "memory");
;             const unsigned og = xb_add(&bar[XB_TOP], 1u);
;             const unsigned tg = og / nx;
;             if (og + 1u == (tg + 1u) * nx) xb_add(&bar[XB_TOPGEN], 1u);
;             else XB_SPIN(xb_ld(&bar[XB_TOPGEN]) == tg, bar);
;             __builtin_amdgcn_fence(__ATOMIC_ACQUIRE, "agent");
;             xb_add(&bar[XB_XGEN(b.x)], 1u);
;             asm volatile("s_waitcnt vmcnt(0)" ::: "memory");
;         } else {
;             XB_SPIN(xb_ld(&bar[XB_XGEN(b.x)]) == gen, bar);
;             __builtin_amdgcn_fence(__ATOMIC_ACQUIRE, "agent");
;             asm volatile("s_waitcnt vmcnt(0)" ::: "memory");
;         }
;     }
;     __syncthreads();
; __global__ void __launch_bounds__(512, 2) fwd_mega(Params P) {
;     ...
;     xcd_barrier(xbar, wid_s);
.LBB0_477:
	s_waitcnt vmcnt(0)
	v_readlane_b32 s0, v255, 29
	s_barrier
	v_mbcnt_lo_u32_b32 v0, -1, 0
	v_mbcnt_hi_u32_b32 v0, -1, v0
	s_nop 0
	v_cmp_eq_u32_e32 vcc, s0, v0
	s_and_saveexec_b64 s[0:1], vcc
	v_readlane_b32 s4, v255, 19
	v_readlane_b32 s10, v255, 25
	v_readlane_b32 s11, v255, 26
	v_readlane_b32 s8, v255, 23
	v_readlane_b32 s9, v255, 24
	s_mov_b64 s[74:75], s[10:11]
	v_readlane_b32 s88, v255, 27
	s_mov_b64 s[72:73], s[8:9]
	v_readlane_b32 s84, v255, 39
	v_readlane_b32 s89, v255, 28
	v_readlane_b32 s87, v255, 30
	v_readlane_b32 s90, v255, 34
	v_readlane_b32 s91, v255, 33
	v_readlane_b32 s5, v255, 20
	v_readlane_b32 s6, v255, 21
	v_readlane_b32 s7, v255, 22
	s_cbranch_execz .LBB0_529
	s_add_i32 s2, 0, 0x25800
	v_mov_b32_e32 v5, s2
	ds_read_b32 v6, v5
	s_lshl_b32 s4, s87, 6
	s_add_u32 s4, s4, 0x1d83d00
	s_add_u32 s4, s80, s4
	s_addc_u32 s5, s81, 0
	v_mov_b32_e32 v2, 0
	v_mov_b32_e32 v3, 1
	global_atomic_add v7, v2, v3, s[4:5] sc0
	s_waitcnt vmcnt(0) lgkmcnt(0)
	v_readfirstlane_b32 s15, v6
	v_readfirstlane_b32 s14, v7
	s_nop 3
	s_add_i32 s14, s14, 1
	s_cmp_eq_u32 s14, s15
	s_cbranch_scc0 .Lb3_notlast
	buffer_wbl2 sc1
	s_waitcnt vmcnt(0)
	s_add_u32 s2, s80, 0x1d83c80
	s_addc_u32 s3, s81, 0
	v_mov_b32_e32 v3, s15
	global_atomic_add v2, v3, s[2:3]
.Lb3_notlast:
	s_add_u32 s2, s80, 0x1d83c80
	s_addc_u32 s3, s81, 0
	s_cmp_lt_u32 s33, 64
	s_cbranch_scc1 .Lb3_prep
	s_add_u32 s2, s80, 0x1d83c40
	s_addc_u32 s3, s81, 0
	s_mov_b32 s12, 32
	s_branch .Lb3_spin0
.Lb3_prep:
	s_mov_b32 s12, 0x100
.Lb3_spin0:
	s_mov_b32 s13, 0
.Lb3_spin:
	global_load_dword v4, v2, s[2:3] sc1
	s_waitcnt vmcnt(0)
	v_readfirstlane_b32 s14, v4
	s_add_i32 s13, s13, 1
	s_cmp_ge_u32 s14, s12
	s_cbranch_scc1 .Lb3_go
	s_sleep 1
	s_cmp_lt_u32 s13, 0x1000
	s_cbranch_scc1 .Lb3_spin
.Lb3_go:
	buffer_inv sc1
	s_waitcnt vmcnt(0)
.LBB0_529:
	s_or_b64 exec, exec, s[0:1]
	s_add_u32 s4, s80, 0x1d83800
	s_addc_u32 s5, s81, 0
	s_add_u32 s6, s80, 0x6000000
	s_addc_u32 s7, s81, 0
	s_add_u32 s8, s80, 0x8000000
	s_addc_u32 s9, s81, 0
	s_add_u32 s10, s80, 0x6030400
	s_mov_b32 s14, 0
	v_readlane_b32 s92, v255, 46
	v_readlane_b32 s62, v255, 42
	v_readlane_b32 s68, v255, 44
	s_addc_u32 s11, s81, 0
	s_mov_b64 s[0:1], -1
	s_mov_b64 s[12:13], 0
	s_mov_b32 s15, 1
	v_mov_b32_e32 v1, 0
	s_mov_b32 s16, 0x3e38aa3b
	s_mov_b32 s17, 0xf149f2ca
	s_mov_b64 s[18:19], 0x20000
	v_mov_b32_e32 v166, 0x358637bd
	s_movk_i32 s40, 0x1000
	s_mov_b64 s[20:21], 0x400
	s_mov_b32 s41, 0x2002000
	s_mov_b32 s42, 0x2004000
	s_mov_b32 s43, 0x2012000
	s_mov_b32 s46, 0x2014000
	s_mov_b64 s[22:23], 0x4000
	s_mov_b64 s[24:25], 0x8000
	v_mov_b32_e32 v167, 0xf149f2ca
	v_mov_b32_e32 v168, 0xb000000
	v_mov_b32_e32 v169, 0xa000000
	v_readlane_b32 s85, v255, 38
	v_readlane_b32 s86, v255, 37
	v_readlane_b32 s93, v255, 47
	v_readlane_b32 s63, v255, 43
	v_readlane_b32 s69, v255, 45
	s_waitcnt lgkmcnt(0)
	s_barrier
	s_branch .LBB0_532
